# interior-chunk prefetch issued by waves 4-7 while they idle in the single-wave cumulative-decay stage (off the LoRA segment's critical path)
# speedup vs baseline: 1.0074x; 1.0074x over previous
; __device__ __forceinline__ void rwkv_chain(LAS unsigned char* lds, int cid, const bf16_t* P0, const float* mu, const float* w0, const float* w2, const float* a0, const float* a2, ...
;     ...
;         __syncthreads();
;         if (cc + 1 < 128) { RW_IDS const int t0n = dir ? (126 - cc) * 32 : (cc + 1) * 32; RW_ISSUE(t0n); }
.LBB0_491:
	v_readfirstlane_b32 s7, v199
	s_cmp_lg_u32 s7, 0
	s_cbranch_scc1 .Lrw_early_ret
	s_cmpk_eq_i32 s46, 0xfe0
	s_waitcnt lgkmcnt(0)
	s_barrier
	s_cbranch_scc1 .LBB0_512
	s_add_i32 s7, s46, 32
	s_and_b64 s[14:15], s[10:11], exec
	s_cselect_b32 s7, s6, s7
	s_mul_i32 s14, s7, 0xe00
	s_ashr_i32 s15, s14, 31
	s_lshl_b64 s[14:15], s[14:15], 1
	s_add_u32 s16, s88, s14
	s_addc_u32 s17, s89, s15
	v_lshl_add_u64 v[8:9], s[16:17], 0, v[40:41]
	v_mov_b32_e32 v14, v200
	v_lshl_add_u64 v[10:11], v[8:9], 0, s[24:25]
	s_cmp_eq_u32 s7, 0
	s_cbranch_scc1 .Lrw_pf_slow
	s_cmpk_eq_i32 s7, 0xfe0
	s_cbranch_scc1 .Lrw_pf_slow
	s_branch .LBB0_512

; __device__ __forceinline__ void rwkv_chain(LAS unsigned char* lds, int cid, const bf16_t* P0, const float* mu, const float* w0, const float* w2, const float* a0, const float* a2, ...
;     ...
;         if (cc + 1 < 128) { RW_IDS const int t0n = dir ? (126 - cc) * 32 : (cc + 1) * 32; RW_ISSUE(t0n); }
.LBB0_516:
	s_or_b64 exec, exec, s[12:13]
	v_readfirstlane_b32 s50, v200
	s_cmpk_lt_u32 s50, 0x100
	s_cbranch_scc1 .Lrw_pf2_done
	s_cmpk_eq_i32 s46, 0xfe0
	s_cbranch_scc1 .Lrw_pf2_done
	s_add_i32 s7, s46, 32
	s_and_b64 vcc, s[10:11], exec
	s_cselect_b32 s7, s6, s7
	s_cmp_eq_u32 s7, 0
	s_cbranch_scc1 .Lrw_pf2_done
	s_cmpk_eq_i32 s7, 0xfe0
	s_cbranch_scc1 .Lrw_pf2_done
	s_mul_i32 s14, s7, 0xe00
	s_ashr_i32 s15, s14, 31
	s_lshl_b64 s[14:15], s[14:15], 1
	s_add_u32 s16, s88, s14
	s_addc_u32 s17, s89, s15
	v_lshl_add_u64 v[8:9], s[16:17], 0, v[40:41]
	v_mov_b32_e32 v14, v200
	v_lshl_add_u64 v[10:11], v[8:9], 0, s[24:25]
	s_mov_b32 s52, 0xffffe400
	s_mov_b32 s53, -1
	s_mov_b64 s[50:51], 0x1c00
	s_mov_b64 s[54:55], 0x2000
	s_mov_b32 s48, 0xfffe4000
	s_mov_b32 s49, -1
	global_load_dwordx2 v[52:53], v[10:11], off
	global_load_dwordx2 v[58:59], v[10:11], off offset:1024
	global_load_dwordx2 v[64:65], v[10:11], off offset:2048
	global_load_dwordx2 v[70:71], v[8:9], off offset:3072
	global_load_dwordx2 v[76:77], v[8:9], off offset:3200
	v_lshl_add_u64 v[12:13], v[10:11], 0, s[52:53]
	v_lshl_add_u64 v[16:17], v[10:11], 0, s[50:51]
	v_lshl_add_u64 v[18:19], v[8:9], 0, s[54:55]
	global_load_dwordx2 v[56:57], v[12:13], off
	global_load_dwordx2 v[60:61], v[12:13], off offset:1024
	global_load_dwordx2 v[66:67], v[12:13], off offset:2048
	global_load_dwordx2 v[72:73], v[8:9], off offset:-4096
	global_load_dwordx2 v[78:79], v[8:9], off offset:-3968
	global_load_dwordx2 v[54:55], v[16:17], off
	global_load_dwordx2 v[62:63], v[16:17], off offset:1024
	global_load_dwordx2 v[68:69], v[16:17], off offset:2048
	global_load_dwordx2 v[74:75], v[18:19], off offset:2048
	global_load_dwordx2 v[80:81], v[18:19], off offset:2176
	v_lshl_add_u64 v[20:21], v[8:9], 0, s[48:49]
	v_lshl_add_u64 v[22:23], v[10:11], 0, s[48:49]
	global_load_dwordx2 v[148:149], v[22:23], off
	global_load_dwordx2 v[154:155], v[22:23], off offset:1024
	global_load_dwordx2 v[160:161], v[22:23], off offset:2048
	global_load_dwordx2 v[166:167], v[20:21], off offset:3072
	global_load_dwordx2 v[172:173], v[20:21], off offset:3200
	v_lshl_add_u64 v[12:13], v[22:23], 0, s[52:53]
	v_lshl_add_u64 v[16:17], v[22:23], 0, s[50:51]
	v_lshl_add_u64 v[18:19], v[20:21], 0, s[54:55]
	global_load_dwordx2 v[152:153], v[12:13], off
	global_load_dwordx2 v[156:157], v[12:13], off offset:1024
	global_load_dwordx2 v[162:163], v[12:13], off offset:2048
	global_load_dwordx2 v[168:169], v[20:21], off offset:-4096
	global_load_dwordx2 v[174:175], v[20:21], off offset:-3968
	global_load_dwordx2 v[150:151], v[16:17], off
	global_load_dwordx2 v[158:159], v[16:17], off offset:1024
	global_load_dwordx2 v[164:165], v[16:17], off offset:2048
	global_load_dwordx2 v[170:171], v[18:19], off offset:2048
	global_load_dwordx2 v[176:177], v[18:19], off offset:2176
	s_and_b64 vcc, exec, s[36:37]
	s_cbranch_vccz .Lrw_pf2_done
	v_and_b32_e32 v12, 15, v14
	v_mul_u32_u24_e32 v12, 6, v12
	v_sub_co_u32_e32 v16, vcc, v8, v12
	v_mov_b32_e32 v13, 0
	s_nop 0
	v_subb_co_u32_e32 v17, vcc, v9, v13, vcc
	v_lshl_add_u64 v[16:17], s[38:39], 1, v[16:17]
	v_lshl_add_u64 v[18:19], v[16:17], 0, s[54:55]
	global_load_ushort v47, v[16:17], off offset:3328
	global_load_ushort v51, v[16:17], off offset:-3840
	global_load_ushort v49, v[18:19], off offset:2304
	v_lshl_add_u64 v[16:17], v[16:17], 0, s[48:49]
	v_lshl_add_u64 v[18:19], v[18:19], 0, s[48:49]
	global_load_ushort v178, v[16:17], off offset:3328
	global_load_ushort v179, v[16:17], off offset:-3840
	global_load_ushort v180, v[18:19], off offset:2304
; __device__ __forceinline__ void rwkv_chain(LAS unsigned char* lds, int cid, const bf16_t* P0, const float* mu, const float* w0, const float* w2, const float* a0, const float* a2, ...
;     ...
;         { RW_IDS const int s = tid >> 4, c0 = (tid & 15) * 4; const int tok = dir ? 31 - s : s, tokp = dir ? tok + 1 : tok - 1;
;           const f32x4 cum = *(const LAS f32x4*)(wS + tok * 64 + c0); f32x4 cump = (f32x4){0.f, 0.f, 0.f, 0.f}; if (s > 0) cump = *(const LAS f32x4*)(wS + tokp * 64 + c0);
;           const f32x4 nk4 = *(const LAS f32x4*)(nkS + tok * 64 + c0), b4 = *(const LAS f32x4*)(bS + tok * 64 + c0), k4 = *(const LAS f32x4*)(kS + tok * 64 + c0), r4 = *(const LAS f32x4*)(rS + tok * 64 + c0), v4 = *(const LAS f32x4*)(vS + tok * 64 + c0);
;           float ta[4], tb[4], tk[4], tr[4];
; #pragma unroll
;           for (int i = 0; i < 4; ++i) { const float g = __expf(cum[i]), gp = __expf(cump[i]), ig = __expf(-cum[i]);
;               ta[i] = nk4[i] * gp; tb[i] = b4[i] * ig; tk[i] = k4[i] * ig; tr[i] = r4[i] * g;
;               BtT[(c0 + i) * 40 + s] = (bf16_t)f2bf(tb[i]); KtT[(c0 + i) * 40 + s] = (bf16_t)f2bf(tk[i]); VT[(c0 + i) * 40 + s] = (bf16_t)f2bf(v4[i]);
;               if (s == 31) gL[c0 + i] = g; }
;           u32x2 w; w.x = pk2(ta[0], ta[1]); w.y = pk2(ta[2], ta[3]); *(LAS u32x2*)(At + s * 72 + c0) = w;
;           w.x = pk2(tb[0], tb[1]); w.y = pk2(tb[2], tb[3]); *(LAS u32x2*)(Bt + s * 72 + c0) = w;
;           w.x = pk2(tk[0], tk[1]); w.y = pk2(tk[2], tk[3]); *(LAS u32x2*)(Kt + s * 72 + c0) = w;
;           w.x = pk2(tr[0], tr[1]); w.y = pk2(tr[2], tr[3]); *(LAS u32x2*)(Rt + s * 72 + c0) = w; }
;         __syncthreads();
;         { RW_IDS const int mat = wid >> 1, mt = wid & 1; const LAS bf16_t* Aop = (mat < 2) ? At : Rt; const LAS bf16_t* Bop = (mat & 1) ? Kt : Bt;
; #pragma unroll
;           for (int nt = 0; nt < 2; ++nt) { f32x4 acc = (f32x4){0.f, 0.f, 0.f, 0.f};
; #pragma unroll
;               for (int ks = 0; ks < 2; ++ks) acc = mfma16(ldsfrag(Bop, 72, nt * 16, ks * 32, fr, fq), ldsfrag(Aop, 72, mt * 16, ks * 32, fr, fq), acc);
;               const int srow = mt * 16 + fr;
; #pragma unroll
;               for (int e = 0; e < 4; ++e) { const int i = nt * 16 + fq * 4 + e; const bool keep = (mat < 2) ? (i < srow) : (i <= srow); if (!keep) acc[e] = 0.f; }
;               if (mat == 0) {
; #pragma unroll
.Lrw_pf2_done:
	v_mov_b32_e32 v8, v200
	s_waitcnt lgkmcnt(0)
	s_barrier
	v_mov_b32_e32 v9, 0
	v_ashrrev_i32_e32 v39, 4, v8
	v_lshlrev_b32_e32 v8, 2, v8
	v_and_b32_e32 v114, 60, v8
	v_sub_u32_e32 v8, 31, v39
	v_cndmask_b32_e64 v12, v39, v8, s[10:11]
	v_lshlrev_b32_e32 v8, 8, v12
	v_lshlrev_b32_e32 v13, 2, v114
	v_add3_u32 v24, 0, v8, v13
	ds_read_b128 v[20:23], v24 offset:24576
	v_cmp_lt_i32_e32 vcc, 0, v39
	v_mov_b32_e32 v8, 0
	v_mov_b32_e32 v10, 0
	v_mov_b32_e32 v11, 0
	s_and_saveexec_b64 s[12:13], vcc
	v_add_lshl_u32 v8, v12, s90, 8
	v_add3_u32 v8, 0, v8, v13
	ds_read_b128 v[8:11], v8 offset:24576
	s_or_b64 exec, exec, s[12:13]
	s_waitcnt lgkmcnt(0)
	v_mul_f32_e32 v115, 0xbfb8aa3b, v20
	v_exp_f32_e32 v116, v115
	ds_read_b128 v[12:15], v24 offset:32768
	ds_read_b128 v[28:31], v24 offset:40960
	ds_read_b128 v[32:35], v24 offset:8192
	ds_read_b128 v[16:19], v24
	ds_read_b128 v[24:27], v24 offset:16384
	v_mul_f32_e32 v20, 0x3fb8aa3b, v20
	v_exp_f32_e32 v115, v20
	s_waitcnt lgkmcnt(3)
	v_mul_f32_e32 v28, v116, v28
	s_waitcnt lgkmcnt(2)
	v_mul_f32_e32 v20, v116, v32
	v_mad_u32_u24 v116, v114, 40, v39
	v_lshl_add_u32 v116, v116, 1, 0
	v_cvt_pk_bf16_f32 v32, v28, s0
	v_add_u32_e32 v117, 0x1c400, v116
	v_cmp_eq_u32_e32 vcc, 31, v39
	ds_write_b16 v117, v32
	v_cvt_pk_bf16_f32 v32, v20, s0
	v_add_u32_e32 v118, 0x1d800, v116
	s_waitcnt lgkmcnt(1)
	v_cvt_pk_bf16_f32 v24, v24, s0
	v_add_u32_e32 v119, 0x1ec00, v116
	v_lshl_add_u32 v116, v114, 2, 0
	ds_write_b16 v118, v32
	ds_write_b16 v119, v24
	s_and_saveexec_b64 s[12:13], vcc
	v_add_u32_e32 v24, 0x25a00, v116
	ds_write_b32 v24, v115
	s_or_b64 exec, exec, s[12:13]
	v_mul_f32_e32 v24, 0xbfb8aa3b, v21
	v_exp_f32_e32 v120, v24
	v_mul_f32_e32 v21, 0x3fb8aa3b, v21
	v_exp_f32_e32 v32, v21
	v_cvt_pk_bf16_f32 v25, v25, s0
	v_mul_f32_e32 v24, v120, v29
	v_mul_f32_e32 v21, v120, v33
	v_cvt_pk_bf16_f32 v29, v24, s0
	ds_write_b16 v117, v29 offset:80
	v_cvt_pk_bf16_f32 v29, v21, s0
	ds_write_b16 v118, v29 offset:80
	ds_write_b16 v119, v25 offset:80
	s_and_saveexec_b64 s[12:13], vcc
	v_add_u32_e32 v25, 0x25a04, v116
	ds_write_b32 v25, v32
	s_or_b64 exec, exec, s[12:13]
	v_mul_f32_e32 v25, 0xbfb8aa3b, v22
	v_exp_f32_e32 v33, v25
	v_mul_f32_e32 v22, 0x3fb8aa3b, v22
	v_exp_f32_e32 v29, v22
	v_cvt_pk_bf16_f32 v26, v26, s0
	v_mul_f32_e32 v25, v33, v30
	v_mul_f32_e32 v22, v33, v34
	v_cvt_pk_bf16_f32 v30, v25, s0
	ds_write_b16 v117, v30 offset:160
	v_cvt_pk_bf16_f32 v30, v22, s0
	ds_write_b16 v118, v30 offset:160
	ds_write_b16 v119, v26 offset:160
	s_and_saveexec_b64 s[12:13], vcc
	v_add_u32_e32 v26, 0x25a08, v116
	ds_write_b32 v26, v29
	s_or_b64 exec, exec, s[12:13]
	v_mul_f32_e32 v26, 0xbfb8aa3b, v23
	v_exp_f32_e32 v33, v26
	v_mul_f32_e32 v23, 0x3fb8aa3b, v23
	v_exp_f32_e32 v30, v23
	v_cvt_pk_bf16_f32 v27, v27, s0
	v_mul_f32_e32 v26, v33, v31
	v_mul_f32_e32 v23, v33, v35
	v_cvt_pk_bf16_f32 v31, v26, s0
	ds_write_b16 v117, v31 offset:240
	v_cvt_pk_bf16_f32 v31, v23, s0
	ds_write_b16 v118, v31 offset:240
	ds_write_b16 v119, v27 offset:240
	s_and_saveexec_b64 s[12:13], vcc
	v_add_u32_e32 v27, 0x25a0c, v116
	ds_write_b32 v27, v30
	s_or_b64 exec, exec, s[12:13]
	v_mul_f32_e32 v11, 0x3fb8aa3b, v11
	v_mul_f32_e32 v10, 0x3fb8aa3b, v10
	v_mul_f32_e32 v9, 0x3fb8aa3b, v9
	v_mul_f32_e32 v8, 0x3fb8aa3b, v8
	v_exp_f32_e32 v11, v11
	v_exp_f32_e32 v10, v10
	v_exp_f32_e32 v9, v9
	v_exp_f32_e32 v8, v8
	v_mul_f32_e32 v11, v15, v11
	v_mul_f32_e32 v10, v14, v10
	v_mul_f32_e32 v9, v13, v9
	v_mul_f32_e32 v8, v12, v8
	v_cvt_pk_bf16_f32 v8, v8, v9
	v_cvt_pk_bf16_f32 v9, v10, v11
	v_mul_lo_u32 v10, v39, s76
	v_lshlrev_b32_e32 v11, 1, v114
	v_mul_f32_e32 v12, v115, v16
	v_add3_u32 v16, s79, v10, v11
	ds_write_b64 v16, v[8:9]
	v_cvt_pk_bf16_f32 v8, v28, v24
	v_cvt_pk_bf16_f32 v9, v25, v26
	v_add3_u32 v16, s80, v10, v11
	v_mul_f32_e32 v15, v30, v19
	v_mul_f32_e32 v14, v29, v18
	v_mul_f32_e32 v13, v32, v17
	ds_write_b64 v16, v[8:9]
	v_cvt_pk_bf16_f32 v8, v20, v21
	v_cvt_pk_bf16_f32 v9, v22, v23
	v_add3_u32 v16, s81, v10, v11
	ds_write_b64 v16, v[8:9]
	v_cvt_pk_bf16_f32 v8, v12, v13
	v_cvt_pk_bf16_f32 v9, v14, v15
	v_add3_u32 v10, s82, v10, v11
	ds_write_b64 v10, v[8:9]
	v_mov_b32_e32 v8, v200
	s_waitcnt lgkmcnt(0)
	s_barrier
	s_nop 0
	v_readfirstlane_b32 s7, v8
	s_ashr_i32 s48, s7, 7
	s_cmp_lt_i32 s48, 2
	s_cselect_b64 s[12:13], -1, 0
	s_and_b64 s[14:15], s[12:13], exec
	v_bfe_u32 v13, v8, 4, 2
	s_cselect_b32 s14, s79, s82
	s_bitcmp0_b32 s7, 7
	s_cselect_b32 s15, s80, s81
	v_lshlrev_b32_e32 v9, 4, v13
	v_add_u32_e32 v11, s15, v9
	s_lshr_b32 s15, s7, 2
	s_cmpk_gt_u32 s7, 0x7f
	s_cselect_b64 s[16:17], -1, 0
	s_cmp_eq_u32 s48, 2
	s_mov_b32 s7, 0x24600
	s_cselect_b32 s7, s7, 0x25000
	s_cmp_lg_u32 s48, 1
	v_and_b32_e32 v10, 15, v8
	s_cselect_b32 s7, s7, 0x23c00
	v_and_or_b32 v8, s15, 16, v10
	v_mov_b32_e32 v12, s14
	s_add_i32 s7, s7, 0
	v_mad_u32_u24 v12, v8, s76, v12
	v_mov_b32_e32 v14, s7
	v_mad_u32_u24 v22, v10, s76, v11
	v_add_u32_e32 v12, v12, v9
	v_mad_u32_u24 v26, v8, s83, v14
	ds_read_b128 v[114:117], v22
	ds_read_b128 v[118:121], v12
	ds_read_b128 v[122:125], v22 offset:64
	ds_read_b128 v[126:129], v12 offset:64
	ds_read_b128 v[130:133], v22 offset:2304
	ds_read_b128 v[134:137], v22 offset:2368
	v_lshlrev_b32_e32 v9, 2, v13
	s_cmp_gt_i32 s48, 1
	s_cselect_b32 s14, 1, 0
	v_lshlrev_b32_e32 v13, 3, v13
	v_sub_u32_e32 v27, v8, v9
	v_add_u32_e32 v13, v26, v13
	v_lshlrev_b32_e32 v28, 5, v8
	v_add_u32_e32 v27, s14, v27
	v_add3_u32 v28, s84, v28, v9
	s_waitcnt lgkmcnt(4)
	v_mfma_f32_16x16x32_bf16 v[14:17], v[114:117], v[118:121], 0
	s_waitcnt lgkmcnt(2)
	v_mfma_f32_16x16x32_bf16 v[14:17], v[122:125], v[126:129], v[14:17]
	s_waitcnt lgkmcnt(1)
	v_mfma_f32_16x16x32_bf16 v[18:21], v[130:133], v[118:121], 0
	s_waitcnt lgkmcnt(0)
	v_mfma_f32_16x16x32_bf16 v[18:21], v[134:137], v[126:129], v[18:21]
	v_cmp_lt_i32_e32 vcc, 0, v27
	v_cmp_lt_i32_e64 s[12:13], 1, v27
	v_cmp_lt_i32_e64 s[14:15], 2, v27
	v_cmp_lt_i32_e64 s[16:17], 3, v27
	v_cndmask_b32_e32 v14, 0, v14, vcc
	v_cndmask_b32_e64 v15, 0, v15, s[12:13]
	v_cndmask_b32_e64 v16, 0, v16, s[14:15]
	v_cndmask_b32_e64 v17, 0, v17, s[16:17]
	v_cmp_lt_i32_e32 vcc, 16, v27
	v_cmp_lt_i32_e64 s[12:13], 17, v27
	v_cmp_lt_i32_e64 s[14:15], 18, v27
	v_cmp_lt_i32_e64 s[16:17], 19, v27
	v_cndmask_b32_e32 v18, 0, v18, vcc
	v_cndmask_b32_e64 v19, 0, v19, s[12:13]
	v_cndmask_b32_e64 v20, 0, v20, s[14:15]
	v_cndmask_b32_e64 v21, 0, v21, s[16:17]
	s_cmp_lg_u32 s48, 0
	s_cbranch_scc0 .Lrw_s1_f32
	v_cvt_pk_bf16_f32 v22, v14, v15
	v_cvt_pk_bf16_f32 v23, v16, v17
	v_cvt_pk_bf16_f32 v24, v18, v19
	v_cvt_pk_bf16_f32 v25, v20, v21
	ds_write_b64 v13, v[22:23]
	ds_write_b64 v13, v[24:25] offset:32
	s_branch .LBB0_534
